# speedup vs baseline: 1.0065x; 1.0008x over previous
.LBB0_426:
	s_cmp_lt_i32 s52, 10
	s_cselect_b64 s[0:1], -1, 0
	s_cmp_gt_i32 s53, 9
	s_cselect_b64 s[2:3], -1, 0
	s_and_b64 s[0:1], s[0:1], s[2:3]
	s_andn2_b64 vcc, exec, s[0:1]
	s_cbranch_vccnz .LBB0_450
	s_cmpk_gt_u32 s33, 0x1ff
	v_mbcnt_lo_u32_b32 v0, -1, 0
	v_mbcnt_hi_u32_b32 v0, -1, v0
	s_cbranch_scc1 .LBB0_440
	s_add_u32 s64, s54, 0xa000000
	s_addc_u32 s65, s55, 0
	s_add_u32 s44, s54, 0x6000000
	s_addc_u32 s45, s55, 0
	s_add_u32 s66, s54, 0x2000000
	s_addc_u32 s67, s55, 0
	s_waitcnt lgkmcnt(0)
	v_readlane_b32 s6, v242, 1
	s_sub_i32 s98, 7, s6
	s_cmp_eq_u32 s98, 0
	s_cbranch_scc1 .Lattn_skew_done
.Lattn_skew:
	s_sleep 48
	s_add_i32 s98, s98, -1
	s_cmp_lg_u32 s98, 0
	s_cbranch_scc1 .Lattn_skew
.Lattn_skew_done:
	s_and_b32 s77, s33, 31
	s_lshl_b32 s68, s6, 5
	s_lshl_b32 s4, s77, 20
	s_add_u32 s2, s44, s4
	s_addc_u32 s3, s45, 0
	s_lshr_b32 s1, s33, 6
	s_and_b32 s1, s1, 6
	s_bfe_u32 s5, s33, 0x10005
	s_or_b32 s1, s1, s5
	s_lshl_b32 s1, s1, 8
	s_and_b32 s0, s33, 64
	s_xor_b32 s5, s1, 0xf00
	s_cmp_eq_u32 s0, 0
	s_cselect_b32 s0, s1, s5
	s_add_i32 s78, s0, s68
	s_mov_b32 s47, 0
	s_lshr_b32 s46, s78, 5
	s_lshl_b64 s[0:1], s[46:47], 13
	s_add_u32 s2, s2, s0
	s_addc_u32 s3, s3, s1
	s_add_u32 s4, s64, s4
	s_addc_u32 s5, s65, 0
	s_add_u32 s0, s4, s0
	v_and_b32_e32 v1, 63, v0
	v_mov_b32_e32 v179, 0
	s_addc_u32 s1, s5, s1
	s_waitcnt vmcnt(0)
	v_lshlrev_b32_e32 v176, 4, v1
	v_mov_b32_e32 v177, v179
	v_lshl_add_u64 v[2:3], s[0:1], 0, v[176:177]
	s_movk_i32 s69, 0x1000
	v_add_co_u32_e32 v2, vcc, s69, v2
	global_load_dwordx4 v[80:83], v176, s[0:1] nt
	global_load_dwordx4 v[84:87], v176, s[0:1] offset:1024 nt
	global_load_dwordx4 v[88:91], v176, s[0:1] offset:2048 nt
	global_load_dwordx4 v[92:95], v176, s[0:1] offset:3072 nt
	v_addc_co_u32_e32 v3, vcc, 0, v3, vcc
	global_load_dwordx4 v[96:99], v[2:3], off nt
	global_load_dwordx4 v[100:103], v[2:3], off offset:1024 nt
	global_load_dwordx4 v[104:107], v[2:3], off offset:2048 nt
	global_load_dwordx4 v[108:111], v[2:3], off offset:3072 nt
	v_lshl_add_u64 v[2:3], s[2:3], 0, v[176:177]
	v_add_co_u32_e32 v2, vcc, s69, v2
	global_load_dwordx4 v[116:119], v176, s[2:3]
	global_load_dwordx4 v[120:123], v176, s[2:3] offset:1024
	global_load_dwordx4 v[128:131], v176, s[2:3] offset:2048
	global_load_dwordx4 v[132:135], v176, s[2:3] offset:3072
	v_addc_co_u32_e32 v3, vcc, 0, v3, vcc
	global_load_dwordx4 v[140:143], v[2:3], off
	global_load_dwordx4 v[136:139], v[2:3], off offset:1024
	global_load_dwordx4 v[124:127], v[2:3], off offset:2048
	global_load_dwordx4 v[112:115], v[2:3], off offset:3072
	s_mul_i32 s2, s6, 0x2200
	v_bfe_u32 v2, v0, 5, 1
	v_cmp_gt_u32_e64 s[0:1], 32, v1
	v_lshlrev_b32_e32 v1, 8, v0
	v_and_b32_e32 v3, 31, v0
	v_lshlrev_b32_e32 v4, 2, v2
	v_and_b32_e32 v182, 0x3000, v1
	s_movk_i32 s3, 0x110
	v_mov_b32_e32 v1, s2
	v_mad_u32_u24 v5, v3, s3, v1
	v_or_b32_e32 v1, 1, v4
	v_cmp_lt_u32_e64 s[4:5], v1, v3
	v_or_b32_e32 v1, 2, v4
	v_cmp_lt_u32_e64 s[6:7], v1, v3
	v_or_b32_e32 v1, 3, v4
	v_cmp_lt_u32_e64 s[8:9], v1, v3
	v_or_b32_e32 v1, 8, v4
	v_cmp_lt_u32_e64 s[10:11], v1, v3
	v_or_b32_e32 v1, 9, v4
	v_cmp_lt_u32_e64 s[12:13], v1, v3
	v_or_b32_e32 v1, 10, v4
	v_cmp_lt_u32_e64 s[14:15], v1, v3
	v_or_b32_e32 v1, 11, v4
	v_cmp_lt_u32_e64 s[16:17], v1, v3
	v_or_b32_e32 v1, 16, v4
	v_cmp_lt_u32_e64 s[18:19], v1, v3
	v_or_b32_e32 v1, 17, v4
	v_cmp_lt_u32_e64 s[20:21], v1, v3
	v_or_b32_e32 v1, 18, v4
	v_cmp_lt_u32_e64 s[22:23], v1, v3
	v_or_b32_e32 v1, 19, v4
	v_cmp_lt_u32_e64 s[24:25], v1, v3
	v_or_b32_e32 v1, 24, v4
	v_cmp_lt_u32_e64 s[26:27], v1, v3
	v_or_b32_e32 v1, 25, v4
	v_cmp_lt_u32_e64 s[28:29], v1, v3
	v_or_b32_e32 v1, 26, v4
	s_add_u32 s56, s50, s90
	v_and_b32_e32 v184, 0xf0, v176
	v_bfe_u32 v0, v0, 4, 2
	v_cmp_lt_u32_e64 s[30:31], v1, v3
	v_or_b32_e32 v1, 27, v4
	s_addc_u32 s57, s51, 0
	v_or_b32_e32 v6, s2, v184
	v_cmp_lt_u32_e64 s[2:3], v4, v3
	v_cmp_lt_u32_e64 s[34:35], v1, v3
	v_mul_u32_u24_e32 v3, 0x110, v0
	v_lshl_add_u64 v[0:1], s[56:57], 0, v[176:177]
	s_mov_b64 s[56:57], 0x14000000
	v_lshlrev_b32_e32 v2, 3, v2
	v_lshl_add_u64 v[186:187], v[0:1], 0, s[56:57]
	s_movk_i32 s56, 0xe000
	v_lshl_add_u64 v[180:181], s[44:45], 0, v[176:177]
	v_mov_b32_e32 v183, v179
	v_mov_b32_e32 v185, v179
	s_mov_b32 s70, 0xc3060000
	s_mov_b32 s57, -1
	v_add_u32_e32 v202, v5, v2
	v_add_u32_e32 v203, v6, v3
	s_movk_i32 s71, 0x4000
	s_mov_b32 s72, 0x8000
	s_mov_b32 s73, 0xc000
	s_mov_b32 s74, 0x10000
	s_mov_b32 s75, 0x14000
	s_mov_b32 s76, 0
	s_branch .LBB0_430

	.amdhsa_kernel _Z14fwd_megakernel6Params
		.amdhsa_group_segment_fixed_size 149504
		.amdhsa_private_segment_fixed_size 0
		.amdhsa_kernarg_size 392
		.amdhsa_user_sgpr_count 2
		.amdhsa_user_sgpr_dispatch_ptr 0
		.amdhsa_user_sgpr_queue_ptr 0
		.amdhsa_user_sgpr_kernarg_segment_ptr 1
		.amdhsa_user_sgpr_dispatch_id 0
		.amdhsa_user_sgpr_kernarg_preload_length 0
		.amdhsa_user_sgpr_kernarg_preload_offset 0
		.amdhsa_user_sgpr_private_segment_size 0
		.amdhsa_uses_dynamic_stack 0
		.amdhsa_enable_private_segment 0
		.amdhsa_system_sgpr_workgroup_id_x 1
		.amdhsa_system_sgpr_workgroup_id_y 0
		.amdhsa_system_sgpr_workgroup_id_z 0
		.amdhsa_system_sgpr_workgroup_info 0
		.amdhsa_system_vgpr_workitem_id 2
		.amdhsa_next_free_vgpr 243
		.amdhsa_next_free_sgpr 100
		.amdhsa_accum_offset 244
		.amdhsa_reserve_vcc 1
		.amdhsa_float_round_mode_32 0
		.amdhsa_float_round_mode_16_64 0
		.amdhsa_float_denorm_mode_32 3
		.amdhsa_float_denorm_mode_16_64 3
		.amdhsa_dx10_clamp 1
		.amdhsa_ieee_mode 1
		.amdhsa_fp16_overflow 0
		.amdhsa_tg_split 0
		.amdhsa_exception_fp_ieee_invalid_op 0
		.amdhsa_exception_fp_denorm_src 0
		.amdhsa_exception_fp_ieee_div_zero 0
		.amdhsa_exception_fp_ieee_overflow 0
		.amdhsa_exception_fp_ieee_underflow 0
		.amdhsa_exception_fp_ieee_inexact 0
		.amdhsa_exception_int_div_zero 0
	.end_amdhsa_kernel

amdhsa.kernels:
  - .agpr_count:     0
    .args:
      - .offset:         0
        .size:           136
        .value_kind:     by_value
      - .offset:         136
        .size:           4
        .value_kind:     hidden_block_count_x
      - .offset:         140
        .size:           4
        .value_kind:     hidden_block_count_y
      - .offset:         144
        .size:           4
        .value_kind:     hidden_block_count_z
      - .offset:         148
        .size:           2
        .value_kind:     hidden_group_size_x
      - .offset:         150
        .size:           2
        .value_kind:     hidden_group_size_y
      - .offset:         152
        .size:           2
        .value_kind:     hidden_group_size_z
      - .offset:         154
        .size:           2
        .value_kind:     hidden_remainder_x
      - .offset:         156
        .size:           2
        .value_kind:     hidden_remainder_y
      - .offset:         158
        .size:           2
        .value_kind:     hidden_remainder_z
      - .offset:         176
        .size:           8
        .value_kind:     hidden_global_offset_x
      - .offset:         184
        .size:           8
        .value_kind:     hidden_global_offset_y
      - .offset:         192
        .size:           8
        .value_kind:     hidden_global_offset_z
      - .offset:         200
        .size:           2
        .value_kind:     hidden_grid_dims
      - .offset:         224
        .size:           8
        .value_kind:     hidden_multigrid_sync_arg
    .group_segment_fixed_size: 149504
    .kernarg_segment_align: 8
    .kernarg_segment_size: 392
    .language:       OpenCL C
    .language_version:
      - 2
      - 0
    .max_flat_workgroup_size: 512
    .name:           _Z14fwd_megakernel6Params
    .private_segment_fixed_size: 0
    .sgpr_count:     106
    .sgpr_spill_count: 5
    .symbol:         _Z14fwd_megakernel6Params.kd
    .uniform_work_group_size: 1
    .uses_dynamic_stack: false
    .vgpr_count:     243
    .vgpr_spill_count: 0
    .wavefront_size: 64
